# row-norm phases: 64-lane sum of squares via DPP adds + readlane instead of six ds_bpermute round trips
# speedup vs baseline: 1.0007x; 1.0007x over previous
; __device__ __forceinline__ unsigned pk2(float lo, float hi) { f32x2 v = {lo, hi}; bf16x2_t b = __builtin_convertvector(v, bf16x2_t); return __builtin_bit_cast(unsigned, b); }
; __device__ __forceinline__ void norm_row_1024(const float* xrow, const float* gain, bf16* orow, int lane) {
;     const f32x4* xr = (const f32x4*)xrow + lane; const f32x4* gr = (const f32x4*)gain + lane;
;     f32x4 v[4]; float s = 0.f;
; #pragma unroll
;     for (int j = 0; j < 4; ++j) { v[j] = xr[64 * j]; s += (v[j].x * v[j].x + v[j].y * v[j].y) + (v[j].z * v[j].z + v[j].w * v[j].w); }
;     const float rstd = 1.0f / sqrtf(wave_sum(s, lane) * (1.f / 1024.f) + EPS);
;     unsigned long long* o8 = (unsigned long long*)orow + lane;
; #pragma unroll
;     for (int j = 0; j < 4; ++j) { const f32x4 g = gr[64 * j];
;         o8[64 * j] = (unsigned long long)pk2(v[j].x * rstd * g.x, v[j].y * rstd * g.y) | ((unsigned long long)pk2(v[j].z * rstd * g.z, v[j].w * rstd * g.w) << 32); }
; }
.LBB0_80:
	global_load_dwordx4 v[20:23], v[10:11], off offset:-3072
	global_load_dwordx4 v[24:27], v[10:11], off offset:-2048
	global_load_dwordx4 v[28:31], v[10:11], off offset:-1024
	global_load_dwordx4 v[32:35], v[10:11], off
	global_load_dwordx4 v[36:39], v[2:3], off
	s_add_i32 s9, s9, s12
	v_lshl_add_u64 v[10:11], v[10:11], 0, s[20:21]
	s_cmp_lt_i32 s9, 0x8000
	s_waitcnt vmcnt(4)
	v_pk_mul_f32 v[40:41], v[22:23], v[22:23]
	v_pk_mul_f32 v[42:43], v[20:21], v[20:21]
	s_waitcnt vmcnt(3)
	v_pk_mul_f32 v[44:45], v[26:27], v[26:27]
	v_pk_mul_f32 v[46:47], v[24:25], v[24:25]
	v_pk_mov_b32 v[52:53], v[42:43], v[40:41] op_sel:[1,0]
	v_mov_b32_e32 v43, v41
	v_pk_mov_b32 v[40:41], v[46:47], v[44:45] op_sel:[1,0]
	v_mov_b32_e32 v47, v45
	s_waitcnt vmcnt(1)
	v_mul_f32_e32 v51, v32, v32
	v_mul_f32_e32 v48, v29, v29
	v_mul_f32_e32 v50, v31, v31
	v_pk_add_f32 v[42:43], v[52:53], v[42:43]
	v_pk_add_f32 v[40:41], v[40:41], v[46:47]
	v_mul_f32_e32 v54, v33, v33
	v_mul_f32_e32 v55, v34, v34
	v_mul_f32_e32 v56, v35, v35
	v_pk_fma_f32 v[44:45], v[28:29], v[28:29], v[48:49] op_sel_hi:[1,1,0]
	v_pk_fma_f32 v[48:49], v[30:31], v[30:31], v[50:51] op_sel_hi:[1,1,0]
	v_pk_add_f32 v[42:43], v[42:43], v[42:43] op_sel:[0,1] op_sel_hi:[1,0]
	v_pk_add_f32 v[40:41], v[40:41], v[40:41] op_sel:[0,1] op_sel_hi:[1,0]
	v_mov_b32_e32 v45, v55
	v_mov_b32_e32 v49, v56
	v_mov_b32_e32 v43, v51
	v_mov_b32_e32 v41, v54
	v_pk_add_f32 v[44:45], v[44:45], v[48:49]
	v_pk_add_f32 v[40:41], v[42:43], v[40:41]
	s_nop 0
	v_pk_add_f32 v[40:41], v[40:41], v[44:45]
	s_nop 0
	v_add_f32_e32 v40, v40, v41
	s_waitcnt lgkmcnt(0)
	s_nop 1
	v_add_f32_dpp v40, v40, v40 quad_perm:[1,0,3,2] row_mask:0xf bank_mask:0xf
	s_nop 1
	v_add_f32_dpp v40, v40, v40 quad_perm:[2,3,0,1] row_mask:0xf bank_mask:0xf
	s_nop 1
	v_add_f32_dpp v40, v40, v40 row_half_mirror row_mask:0xf bank_mask:0xf
	s_nop 1
	v_add_f32_dpp v40, v40, v40 row_mirror row_mask:0xf bank_mask:0xf
	s_nop 1
	v_add_f32_dpp v40, v40, v40 row_bcast:15 row_mask:0xa bank_mask:0xf
	s_nop 1
	v_add_f32_dpp v40, v40, v40 row_bcast:31 row_mask:0xc bank_mask:0xf
	s_nop 1
	v_readlane_b32 s98, v40, 63
	s_nop 3
	v_mov_b32_e32 v40, s98
	v_fmamk_f32 v40, v40, 0x3a800000, v1
	v_mul_f32_e32 v41, 0x4f800000, v40
	v_cmp_gt_f32_e32 vcc, s3, v40
	s_nop 1
	v_cndmask_b32_e32 v40, v40, v41, vcc
	v_sqrt_f32_e32 v41, v40
	s_nop 0
	v_add_u32_e32 v42, -1, v41
	v_add_u32_e32 v43, 1, v41
	v_fma_f32 v44, -v42, v41, v40
	v_fma_f32 v45, -v43, v41, v40
	v_cmp_ge_f32_e64 s[4:5], 0, v44
	s_nop 1
	v_cndmask_b32_e64 v41, v41, v42, s[4:5]
	v_cmp_lt_f32_e64 s[4:5], 0, v45
	s_nop 1
	v_cndmask_b32_e64 v41, v41, v43, s[4:5]
	v_mul_f32_e32 v42, 0x37800000, v41
	v_cndmask_b32_e32 v41, v41, v42, vcc
	v_cmp_class_f32_e32 vcc, v40, v19
	s_nop 1
	v_cndmask_b32_e32 v40, v41, v40, vcc
	v_div_scale_f32 v41, s[4:5], v40, v40, 1.0
	v_rcp_f32_e32 v43, v41
	v_div_scale_f32 v42, vcc, 1.0, v40, 1.0
	v_fma_f32 v44, -v41, v43, 1.0
	v_fmac_f32_e32 v43, v44, v43
	v_mul_f32_e32 v44, v42, v43
	v_fma_f32 v45, -v41, v44, v42
	v_fmac_f32_e32 v44, v45, v43
	v_fma_f32 v41, -v41, v44, v42
	v_div_fmas_f32 v41, v41, v43, v44
	v_div_fixup_f32 v40, v41, v40, 1.0
	v_pk_mul_f32 v[20:21], v[20:21], v[40:41] op_sel_hi:[1,0]
	v_pk_mul_f32 v[22:23], v[22:23], v[40:41] op_sel_hi:[1,0]
	s_waitcnt vmcnt(0)
	v_pk_mul_f32 v[20:21], v[36:37], v[20:21]
	v_pk_mul_f32 v[22:23], v[38:39], v[22:23]
	v_cvt_pk_bf16_f32 v20, v20, v21
	v_cvt_pk_bf16_f32 v21, v22, v23
	global_store_dwordx2 v[8:9], v[20:21], off
	global_load_dwordx4 v[20:23], v[2:3], off offset:1024
	v_pk_mul_f32 v[24:25], v[24:25], v[40:41] op_sel_hi:[1,0]
	v_pk_mul_f32 v[26:27], v[26:27], v[40:41] op_sel_hi:[1,0]
	s_waitcnt vmcnt(0)
	v_pk_mul_f32 v[20:21], v[20:21], v[24:25]
	v_pk_mul_f32 v[22:23], v[22:23], v[26:27]
	v_cvt_pk_bf16_f32 v20, v20, v21
	v_cvt_pk_bf16_f32 v21, v22, v23
	global_store_dwordx2 v[8:9], v[20:21], off offset:512
	global_load_dwordx4 v[20:23], v[2:3], off offset:2048
	v_pk_mul_f32 v[24:25], v[28:29], v[40:41] op_sel_hi:[1,0]
	v_pk_mul_f32 v[26:27], v[30:31], v[40:41] op_sel_hi:[1,0]
	s_waitcnt vmcnt(0)
	v_pk_mul_f32 v[20:21], v[20:21], v[24:25]
	v_pk_mul_f32 v[22:23], v[22:23], v[26:27]
	v_cvt_pk_bf16_f32 v20, v20, v21
	v_cvt_pk_bf16_f32 v21, v22, v23
	global_store_dwordx2 v[8:9], v[20:21], off offset:1024
	global_load_dwordx4 v[20:23], v[2:3], off offset:3072
	v_pk_mul_f32 v[24:25], v[32:33], v[40:41] op_sel_hi:[1,0]
	v_pk_mul_f32 v[26:27], v[34:35], v[40:41] op_sel_hi:[1,0]
	s_waitcnt vmcnt(0)
	v_pk_mul_f32 v[20:21], v[20:21], v[24:25]
	v_pk_mul_f32 v[22:23], v[22:23], v[26:27]
	v_cvt_pk_bf16_f32 v20, v20, v21
	v_cvt_pk_bf16_f32 v21, v22, v23
	global_store_dwordx2 v[8:9], v[20:21], off offset:1536
	v_lshl_add_u64 v[8:9], v[8:9], 0, s[18:19]
	s_cbranch_scc1 .LBB0_80

; __device__ __forceinline__ unsigned pk2(float lo, float hi) { f32x2 v = {lo, hi}; bf16x2_t b = __builtin_convertvector(v, bf16x2_t); return __builtin_bit_cast(unsigned, b); }
; #define INP(i) (*(const float* const volatile __attribute__((address_space(4)))*)((const __attribute__((address_space(4))) char*)__builtin_amdgcn_kernarg_segment_ptr() + 8 * (i)))
; __device__ __forceinline__ void norm_row_1024(const float* xrow, const float* gain, bf16* orow, int lane) {
;     const f32x4* xr = (const f32x4*)xrow + lane; const f32x4* gr = (const f32x4*)gain + lane;
;     f32x4 v[4]; float s = 0.f;
; #pragma unroll
;     for (int j = 0; j < 4; ++j) { v[j] = xr[64 * j]; s += (v[j].x * v[j].x + v[j].y * v[j].y) + (v[j].z * v[j].z + v[j].w * v[j].w); }
;     const float rstd = 1.0f / sqrtf(wave_sum(s, lane) * (1.f / 1024.f) + EPS);
;     unsigned long long* o8 = (unsigned long long*)orow + lane;
; #pragma unroll
;     for (int j = 0; j < 4; ++j) { const f32x4 g = gr[64 * j];
;         o8[64 * j] = (unsigned long long)pk2(v[j].x * rstd * g.x, v[j].y * rstd * g.y) | ((unsigned long long)pk2(v[j].z * rstd * g.z, v[j].w * rstd * g.w) << 32); }
; }
; __global__ void __launch_bounds__(NTHREADS, 2) mega_fwd(Args args) {
;     ...
;         for (int it = gw; it < 2 * 512; it += NGW) { const int ly = it >> 9, r = it & 511;
;             norm_row_1024(mem + (size_t)r * DM, INP(22) + ly * DM, (bf16*)(ws + S_MN) + ((size_t)ly * 512 + r) * DM, lane); }
.LBB0_83:
	s_and_b32 s9, s8, 0x1ff
	s_lshl_b32 s10, s9, 12
	v_lshl_add_u64 v[14:15], v[0:1], 0, s[10:11]
	s_load_dwordx2 s[4:5], s[82:83], 0xb0
	global_load_dwordx4 v[18:21], v[14:15], off
	global_load_dwordx4 v[22:25], v[14:15], off offset:1024
	global_load_dwordx4 v[26:29], v[14:15], off offset:2048
	global_load_dwordx4 v[30:33], v[14:15], off offset:3072
	s_ashr_i32 s20, s8, 9
	s_lshl_b32 s18, s20, 10
	s_ashr_i32 s19, s18, 31
	s_lshl_b64 s[18:19], s[18:19], 2
	s_waitcnt lgkmcnt(0)
	s_add_u32 s18, s4, s18
	s_addc_u32 s19, s5, s19
	global_load_dwordx4 v[34:37], v11, s[18:19]
	s_ashr_i32 s21, s20, 31
	s_lshl_b64 s[4:5], s[20:21], 20
	s_add_u32 s4, s54, s4
	s_addc_u32 s5, s55, s5
	s_lshl_b32 s9, s9, 11
	s_add_u32 s20, s4, s9
	s_addc_u32 s21, s5, 0
	s_add_i32 s8, s8, s12
	s_cmpk_gt_i32 s8, 0x3ff
	s_waitcnt vmcnt(4)
	v_pk_mul_f32 v[14:15], v[20:21], v[20:21]
	v_pk_mul_f32 v[38:39], v[18:19], v[18:19]
	s_waitcnt vmcnt(3)
	v_pk_mul_f32 v[40:41], v[24:25], v[24:25]
	v_pk_mul_f32 v[42:43], v[22:23], v[22:23]
	v_pk_mov_b32 v[46:47], v[38:39], v[14:15] op_sel:[1,0]
	v_mov_b32_e32 v39, v15
	v_pk_mov_b32 v[14:15], v[42:43], v[40:41] op_sel:[1,0]
	v_mov_b32_e32 v43, v41
	s_waitcnt vmcnt(2)
	v_mul_f32_e32 v16, v27, v27
	v_mul_f32_e32 v44, v29, v29
	v_pk_add_f32 v[38:39], v[46:47], v[38:39]
	v_pk_add_f32 v[14:15], v[14:15], v[42:43]
	s_waitcnt vmcnt(1)
	v_mul_f32_e32 v48, v30, v30
	v_mul_f32_e32 v49, v31, v31
	v_mul_f32_e32 v50, v32, v32
	v_mul_f32_e32 v51, v33, v33
	v_pk_fma_f32 v[40:41], v[26:27], v[26:27], v[16:17] op_sel_hi:[1,1,0]
	v_pk_fma_f32 v[44:45], v[28:29], v[28:29], v[44:45] op_sel_hi:[1,1,0]
	v_pk_add_f32 v[38:39], v[38:39], v[38:39] op_sel:[0,1] op_sel_hi:[1,0]
	v_pk_add_f32 v[14:15], v[14:15], v[14:15] op_sel:[0,1] op_sel_hi:[1,0]
	v_mov_b32_e32 v41, v50
	v_mov_b32_e32 v45, v51
	v_mov_b32_e32 v39, v48
	v_mov_b32_e32 v15, v49
	v_pk_add_f32 v[40:41], v[40:41], v[44:45]
	v_pk_add_f32 v[14:15], v[38:39], v[14:15]
	s_nop 0
	v_pk_add_f32 v[14:15], v[14:15], v[40:41]
	s_nop 0
	v_add_f32_e32 v14, v14, v15
	s_waitcnt lgkmcnt(0)
	s_nop 1
	v_add_f32_dpp v14, v14, v14 quad_perm:[1,0,3,2] row_mask:0xf bank_mask:0xf
	s_nop 1
	v_add_f32_dpp v14, v14, v14 quad_perm:[2,3,0,1] row_mask:0xf bank_mask:0xf
	s_nop 1
	v_add_f32_dpp v14, v14, v14 row_half_mirror row_mask:0xf bank_mask:0xf
	s_nop 1
	v_add_f32_dpp v14, v14, v14 row_mirror row_mask:0xf bank_mask:0xf
	s_nop 1
	v_add_f32_dpp v14, v14, v14 row_bcast:15 row_mask:0xa bank_mask:0xf
	s_nop 1
	v_add_f32_dpp v14, v14, v14 row_bcast:31 row_mask:0xc bank_mask:0xf
	s_nop 1
	v_readlane_b32 s98, v14, 63
	s_nop 3
	v_mov_b32_e32 v14, s98
	v_fmamk_f32 v14, v14, 0x3a800000, v12
	v_mul_f32_e32 v15, 0x4f800000, v14
	v_cmp_gt_f32_e32 vcc, s3, v14
	s_nop 1
	v_cndmask_b32_e32 v14, v14, v15, vcc
	v_sqrt_f32_e32 v15, v14
	s_nop 0
	v_add_u32_e32 v16, -1, v15
	v_add_u32_e32 v38, 1, v15
	v_fma_f32 v39, -v16, v15, v14
	v_fma_f32 v40, -v38, v15, v14
	v_cmp_ge_f32_e64 s[4:5], 0, v39
	s_nop 1
	v_cndmask_b32_e64 v15, v15, v16, s[4:5]
	v_cmp_lt_f32_e64 s[4:5], 0, v40
	s_nop 1
	v_cndmask_b32_e64 v15, v15, v38, s[4:5]
	v_mul_f32_e32 v16, 0x37800000, v15
	v_cndmask_b32_e32 v15, v15, v16, vcc
	v_cmp_class_f32_e32 vcc, v14, v13
	s_nop 1
	v_cndmask_b32_e32 v14, v15, v14, vcc
	v_div_scale_f32 v15, s[4:5], v14, v14, 1.0
	v_rcp_f32_e32 v38, v15
	v_div_scale_f32 v16, vcc, 1.0, v14, 1.0
	v_fma_f32 v39, -v15, v38, 1.0
	v_fmac_f32_e32 v38, v39, v38
	v_mul_f32_e32 v39, v16, v38
	v_fma_f32 v40, -v15, v39, v16
	v_fmac_f32_e32 v39, v40, v38
	v_fma_f32 v15, -v15, v39, v16
	v_div_fmas_f32 v15, v15, v38, v39
	v_div_fixup_f32 v14, v15, v14, 1.0
	v_pk_mul_f32 v[18:19], v[18:19], v[14:15] op_sel_hi:[1,0]
	v_pk_mul_f32 v[20:21], v[20:21], v[14:15] op_sel_hi:[1,0]
	s_waitcnt vmcnt(0)
	v_pk_mul_f32 v[18:19], v[34:35], v[18:19]
	v_pk_mul_f32 v[20:21], v[36:37], v[20:21]
	v_cvt_pk_bf16_f32 v18, v18, v19
	v_cvt_pk_bf16_f32 v19, v20, v21
	global_store_dwordx2 v4, v[18:19], s[20:21]
	global_load_dwordx4 v[18:21], v11, s[18:19] offset:1024
	v_pk_mul_f32 v[22:23], v[22:23], v[14:15] op_sel_hi:[1,0]
	v_pk_mul_f32 v[24:25], v[24:25], v[14:15] op_sel_hi:[1,0]
	s_waitcnt vmcnt(0)
	v_pk_mul_f32 v[18:19], v[18:19], v[22:23]
	v_pk_mul_f32 v[20:21], v[20:21], v[24:25]
	v_cvt_pk_bf16_f32 v18, v18, v19
	v_cvt_pk_bf16_f32 v19, v20, v21
	global_store_dwordx2 v4, v[18:19], s[20:21] offset:512
	global_load_dwordx4 v[18:21], v11, s[18:19] offset:2048
	v_pk_mul_f32 v[22:23], v[26:27], v[14:15] op_sel_hi:[1,0]
	v_pk_mul_f32 v[24:25], v[28:29], v[14:15] op_sel_hi:[1,0]
	s_waitcnt vmcnt(0)
	v_pk_mul_f32 v[18:19], v[18:19], v[22:23]
	v_pk_mul_f32 v[20:21], v[20:21], v[24:25]
	v_cvt_pk_bf16_f32 v18, v18, v19
	v_cvt_pk_bf16_f32 v19, v20, v21
	global_store_dwordx2 v4, v[18:19], s[20:21] offset:1024
	global_load_dwordx4 v[18:21], v11, s[18:19] offset:3072
	v_pk_mul_f32 v[22:23], v[30:31], v[14:15] op_sel_hi:[1,0]
	v_pk_mul_f32 v[14:15], v[32:33], v[14:15] op_sel_hi:[1,0]
	s_waitcnt vmcnt(0)
	v_pk_mul_f32 v[18:19], v[18:19], v[22:23]
	v_pk_mul_f32 v[14:15], v[20:21], v[14:15]
	v_cvt_pk_bf16_f32 v18, v18, v19
	v_cvt_pk_bf16_f32 v19, v14, v15
	global_store_dwordx2 v4, v[18:19], s[20:21] offset:1536
	s_cbranch_scc0 .LBB0_83

; __device__ __forceinline__ void norm_row_1024_h(const bf16* xrow, const float* gain, bf16* orow, int lane) {
;     u32x4 v[2]; float s = 0.f;
; #pragma unroll
;     for (int j = 0; j < 2; ++j) { v[j] = ((const u32x4*)xrow)[lane + 64 * j]; s += chunk_ss(v[j]); }
;     const float rstd = 1.0f / sqrtf(wave_sum(s, lane) * (1.f / 1024.f) + EPS);
; #pragma unroll
;     for (int j = 0; j < 2; ++j) ((u32x4*)orow)[lane + 64 * j] = chunk_scale(v[j], rstd, gain + 8 * (lane + 64 * j));
; }
; __device__ __forceinline__ void norm_phase_h(const bf16* X, const float* gain, bf16* XN, int gw, int NGW, int lane) {
;     for (int m = gw; m < T; m += NGW) norm_row_1024_h(X + (size_t)m * DM, gain, XN + (size_t)m * DM, lane);
.LBB0_731:
	global_load_dwordx4 v[2:5], v[10:11], off offset:-1024
	global_load_dwordx4 v[28:31], v[10:11], off
	global_load_dwordx4 v[32:35], v[6:7], off offset:16
	global_load_dwordx4 v[36:39], v[6:7], off
	s_brev_b32 s20, 15
	s_add_i32 s2, s2, s6
	s_cmp_lt_i32 s2, 0x8000
	s_waitcnt vmcnt(0)
	v_and_b32_e32 v43, 0xffff0000, v2
	v_and_b32_e32 v19, 0xffff0000, v28
	v_lshlrev_b32_e32 v42, 16, v2
	v_lshlrev_b32_e32 v18, 16, v28
	v_mov_b32_e32 v52, v43
	v_mov_b32_e32 v53, v19
	v_lshlrev_b32_e32 v40, 16, v4
	v_and_b32_e32 v41, 0xffff0000, v4
	v_lshlrev_b32_e32 v4, 16, v3
	v_lshlrev_b32_e32 v16, 16, v29
	v_and_b32_e32 v17, 0xffff0000, v29
	v_mov_b32_e32 v28, v42
	v_mov_b32_e32 v29, v18
	v_pk_mul_f32 v[52:53], v[52:53], v[52:53]
	v_lshlrev_b32_e32 v20, 16, v5
	v_and_b32_e32 v21, 0xffff0000, v5
	v_and_b32_e32 v5, 0xffff0000, v3
	v_mov_b32_e32 v48, v4
	v_mov_b32_e32 v49, v16
	v_pk_fma_f32 v[28:29], v[28:29], v[28:29], v[52:53]
	v_lshlrev_b32_e32 v14, 16, v30
	v_mov_b32_e32 v50, v5
	v_mov_b32_e32 v51, v17
	v_pk_fma_f32 v[28:29], v[48:49], v[48:49], v[28:29]
	v_lshlrev_b32_e32 v12, 16, v31
	v_and_b32_e32 v13, 0xffff0000, v31
	v_and_b32_e32 v15, 0xffff0000, v30
	v_mov_b32_e32 v30, v40
	v_mov_b32_e32 v31, v14
	v_pk_fma_f32 v[28:29], v[50:51], v[50:51], v[28:29]
	v_mov_b32_e32 v46, v41
	v_mov_b32_e32 v47, v15
	v_pk_fma_f32 v[28:29], v[30:31], v[30:31], v[28:29]
	v_mov_b32_e32 v2, v20
	v_mov_b32_e32 v3, v12
	v_pk_fma_f32 v[28:29], v[46:47], v[46:47], v[28:29]
	v_mov_b32_e32 v44, v21
	v_mov_b32_e32 v45, v13
	v_pk_fma_f32 v[2:3], v[2:3], v[2:3], v[28:29]
	s_nop 0
	v_pk_fma_f32 v[2:3], v[44:45], v[44:45], v[2:3]
	s_nop 0
	v_add_f32_e32 v0, v2, v3
	s_waitcnt lgkmcnt(0)
	s_nop 1
	v_add_f32_dpp v0, v0, v0 quad_perm:[1,0,3,2] row_mask:0xf bank_mask:0xf
	s_nop 1
	v_add_f32_dpp v0, v0, v0 quad_perm:[2,3,0,1] row_mask:0xf bank_mask:0xf
	s_nop 1
	v_add_f32_dpp v0, v0, v0 row_half_mirror row_mask:0xf bank_mask:0xf
	s_nop 1
	v_add_f32_dpp v0, v0, v0 row_mirror row_mask:0xf bank_mask:0xf
	s_nop 1
	v_add_f32_dpp v0, v0, v0 row_bcast:15 row_mask:0xa bank_mask:0xf
	s_nop 1
	v_add_f32_dpp v0, v0, v0 row_bcast:31 row_mask:0xc bank_mask:0xf
	s_nop 1
	v_readlane_b32 s98, v0, 63
	s_nop 3
	v_mov_b32_e32 v0, s98
	v_fmamk_f32 v0, v0, 0x3a800000, v214
	v_cmp_gt_f32_e32 vcc, s33, v0
	v_mul_f32_e32 v2, 0x4f800000, v0
	s_nop 0
	v_cndmask_b32_e32 v0, v0, v2, vcc
	v_sqrt_f32_e32 v2, v0
	s_nop 0
	v_add_u32_e32 v3, -1, v2
	v_fma_f32 v28, -v3, v2, v0
	v_cmp_ge_f32_e64 s[40:41], 0, v28
	v_add_u32_e32 v28, 1, v2
	s_nop 0
	v_cndmask_b32_e64 v3, v2, v3, s[40:41]
	v_fma_f32 v2, -v28, v2, v0
	v_cmp_lt_f32_e64 s[40:41], 0, v2
	s_nop 1
	v_cndmask_b32_e64 v2, v3, v28, s[40:41]
	v_mul_f32_e32 v3, 0x37800000, v2
	v_cndmask_b32_e32 v2, v2, v3, vcc
	v_cmp_class_f32_e32 vcc, v0, v215
	s_nop 1
	v_cndmask_b32_e32 v0, v2, v0, vcc
	v_div_scale_f32 v2, s[4:5], v0, v0, 1.0
	v_rcp_f32_e32 v3, v2
	s_nop 0
	v_fma_f32 v28, -v2, v3, 1.0
	v_fmac_f32_e32 v3, v28, v3
	v_div_scale_f32 v28, vcc, 1.0, v0, 1.0
	v_mul_f32_e32 v29, v28, v3
	v_fma_f32 v30, -v2, v29, v28
	v_fmac_f32_e32 v29, v30, v3
	v_fma_f32 v2, -v2, v29, v28
	v_div_fmas_f32 v2, v2, v3, v29
	v_div_fixup_f32 v0, v2, v0, 1.0
	v_pk_mul_f32 v[2:3], v[36:37], v[0:1] op_sel_hi:[1,0]
	v_pk_mul_f32 v[28:29], v[38:39], v[0:1] op_sel_hi:[1,0]
	v_pk_mul_f32 v[30:31], v[34:35], v[0:1] op_sel_hi:[1,0]
	v_pk_mul_f32 v[2:3], v[2:3], v[42:43]
	v_pk_mul_f32 v[4:5], v[28:29], v[4:5]
	v_pk_mul_f32 v[28:29], v[32:33], v[0:1] op_sel_hi:[1,0]
	v_pk_mul_f32 v[20:21], v[30:31], v[20:21]
	v_pk_mul_f32 v[28:29], v[28:29], v[40:41]
	v_cvt_pk_bf16_f32 v2, v2, v3
	v_cvt_pk_bf16_f32 v3, v4, v5
	v_cvt_pk_bf16_f32 v5, v20, v21
	v_add_co_u32_e32 v20, vcc, s20, v10
	v_cvt_pk_bf16_f32 v4, v28, v29
	s_nop 0
	v_addc_co_u32_e32 v21, vcc, -1, v11, vcc
	global_store_dwordx4 v[20:21], v[2:5], off offset:-1024
	global_load_dwordx4 v[2:5], v[8:9], off offset:16
	s_nop 0
	global_load_dwordx4 v[28:31], v[8:9], off
	v_lshl_add_u64 v[10:11], v[10:11], 0, s[8:9]
	s_waitcnt vmcnt(1)
	v_pk_mul_f32 v[2:3], v[2:3], v[0:1] op_sel_hi:[1,0]
	s_waitcnt vmcnt(0)
	v_pk_mul_f32 v[28:29], v[28:29], v[0:1] op_sel_hi:[1,0]
	v_pk_mul_f32 v[14:15], v[2:3], v[14:15]
	v_pk_mul_f32 v[18:19], v[28:29], v[18:19]
	v_pk_mul_f32 v[28:29], v[30:31], v[0:1] op_sel_hi:[1,0]
	v_pk_mul_f32 v[2:3], v[4:5], v[0:1] op_sel_hi:[1,0]
	v_pk_mul_f32 v[16:17], v[28:29], v[16:17]
	v_pk_mul_f32 v[12:13], v[2:3], v[12:13]
	v_cvt_pk_bf16_f32 v2, v18, v19
	v_cvt_pk_bf16_f32 v3, v16, v17
	v_cvt_pk_bf16_f32 v4, v14, v15
	v_cvt_pk_bf16_f32 v5, v12, v13
	global_store_dwordx4 v[20:21], v[2:5], off
	s_cbranch_scc1 .LBB0_731

; __device__ __forceinline__ void norm_row_1024_h(const bf16* xrow, const float* gain, bf16* orow, int lane) {
;     u32x4 v[2]; float s = 0.f;
; #pragma unroll
;     for (int j = 0; j < 2; ++j) { v[j] = ((const u32x4*)xrow)[lane + 64 * j]; s += chunk_ss(v[j]); }
;     const float rstd = 1.0f / sqrtf(wave_sum(s, lane) * (1.f / 1024.f) + EPS);
; #pragma unroll
;     for (int j = 0; j < 2; ++j) ((u32x4*)orow)[lane + 64 * j] = chunk_scale(v[j], rstd, gain + 8 * (lane + 64 * j));
; }
; __device__ __forceinline__ void norm_phase_h(const bf16* X, const float* gain, bf16* XN, int gw, int NGW, int lane) {
;     for (int m = gw; m < T; m += NGW) norm_row_1024_h(X + (size_t)m * DM, gain, XN + (size_t)m * DM, lane);
.LBB0_1149:
	global_load_dwordx4 v[2:5], v[10:11], off offset:-1024
	global_load_dwordx4 v[28:31], v[10:11], off
	global_load_dwordx4 v[32:35], v[6:7], off offset:16
	global_load_dwordx4 v[36:39], v[6:7], off
	s_add_i32 s2, s2, s10
	s_cmp_lt_i32 s2, 0x8000
	s_waitcnt vmcnt(3)
	v_and_b32_e32 v43, 0xffff0000, v2
	s_waitcnt vmcnt(2)
	v_and_b32_e32 v19, 0xffff0000, v28
	v_lshlrev_b32_e32 v42, 16, v2
	v_lshlrev_b32_e32 v18, 16, v28
	v_mov_b32_e32 v52, v43
	v_mov_b32_e32 v53, v19
	v_lshlrev_b32_e32 v40, 16, v4
	v_and_b32_e32 v41, 0xffff0000, v4
	v_lshlrev_b32_e32 v4, 16, v3
	v_lshlrev_b32_e32 v16, 16, v29
	v_and_b32_e32 v17, 0xffff0000, v29
	v_mov_b32_e32 v28, v42
	v_mov_b32_e32 v29, v18
	v_pk_mul_f32 v[52:53], v[52:53], v[52:53]
	v_lshlrev_b32_e32 v20, 16, v5
	v_and_b32_e32 v21, 0xffff0000, v5
	v_and_b32_e32 v5, 0xffff0000, v3
	v_mov_b32_e32 v48, v4
	v_mov_b32_e32 v49, v16
	v_pk_fma_f32 v[28:29], v[28:29], v[28:29], v[52:53]
	v_lshlrev_b32_e32 v14, 16, v30
	v_mov_b32_e32 v50, v5
	v_mov_b32_e32 v51, v17
	v_pk_fma_f32 v[28:29], v[48:49], v[48:49], v[28:29]
	v_lshlrev_b32_e32 v12, 16, v31
	v_and_b32_e32 v13, 0xffff0000, v31
	v_and_b32_e32 v15, 0xffff0000, v30
	v_mov_b32_e32 v30, v40
	v_mov_b32_e32 v31, v14
	v_pk_fma_f32 v[28:29], v[50:51], v[50:51], v[28:29]
	v_mov_b32_e32 v46, v41
	v_mov_b32_e32 v47, v15
	v_pk_fma_f32 v[28:29], v[30:31], v[30:31], v[28:29]
	v_mov_b32_e32 v2, v20
	v_mov_b32_e32 v3, v12
	v_pk_fma_f32 v[28:29], v[46:47], v[46:47], v[28:29]
	v_mov_b32_e32 v44, v21
	v_mov_b32_e32 v45, v13
	v_pk_fma_f32 v[2:3], v[2:3], v[2:3], v[28:29]
	s_nop 0
	v_pk_fma_f32 v[2:3], v[44:45], v[44:45], v[2:3]
	s_nop 0
	v_add_f32_e32 v0, v2, v3
	s_waitcnt lgkmcnt(0)
	s_nop 1
	v_add_f32_dpp v0, v0, v0 quad_perm:[1,0,3,2] row_mask:0xf bank_mask:0xf
	s_nop 1
	v_add_f32_dpp v0, v0, v0 quad_perm:[2,3,0,1] row_mask:0xf bank_mask:0xf
	s_nop 1
	v_add_f32_dpp v0, v0, v0 row_half_mirror row_mask:0xf bank_mask:0xf
	s_nop 1
	v_add_f32_dpp v0, v0, v0 row_mirror row_mask:0xf bank_mask:0xf
	s_nop 1
	v_add_f32_dpp v0, v0, v0 row_bcast:15 row_mask:0xa bank_mask:0xf
	s_nop 1
	v_add_f32_dpp v0, v0, v0 row_bcast:31 row_mask:0xc bank_mask:0xf
	s_nop 1
	v_readlane_b32 s98, v0, 63
	s_nop 3
	v_mov_b32_e32 v0, s98
	v_fmamk_f32 v0, v0, 0x3a800000, v214
	v_cmp_gt_f32_e32 vcc, s33, v0
	v_mul_f32_e32 v2, 0x4f800000, v0
	s_nop 0
	v_cndmask_b32_e32 v0, v0, v2, vcc
	v_sqrt_f32_e32 v2, v0
	s_nop 0
	v_add_u32_e32 v3, -1, v2
	v_fma_f32 v28, -v3, v2, v0
	v_cmp_ge_f32_e64 s[6:7], 0, v28
	v_add_u32_e32 v28, 1, v2
	s_nop 0
	v_cndmask_b32_e64 v3, v2, v3, s[6:7]
	v_fma_f32 v2, -v28, v2, v0
	v_cmp_lt_f32_e64 s[6:7], 0, v2
	s_nop 1
	v_cndmask_b32_e64 v2, v3, v28, s[6:7]
	v_mul_f32_e32 v3, 0x37800000, v2
	v_cndmask_b32_e32 v2, v2, v3, vcc
	v_cmp_class_f32_e32 vcc, v0, v215
	s_nop 1
	v_cndmask_b32_e32 v0, v2, v0, vcc
	v_div_scale_f32 v2, s[4:5], v0, v0, 1.0
	v_rcp_f32_e32 v3, v2
	s_nop 0
	v_fma_f32 v28, -v2, v3, 1.0
	v_fmac_f32_e32 v3, v28, v3
	v_div_scale_f32 v28, vcc, 1.0, v0, 1.0
	v_mul_f32_e32 v29, v28, v3
	v_fma_f32 v30, -v2, v29, v28
	v_fmac_f32_e32 v29, v30, v3
	v_fma_f32 v2, -v2, v29, v28
	v_div_fmas_f32 v2, v2, v3, v29
	v_div_fixup_f32 v0, v2, v0, 1.0
	s_waitcnt vmcnt(0)
	v_pk_mul_f32 v[2:3], v[36:37], v[0:1] op_sel_hi:[1,0]
	v_pk_mul_f32 v[28:29], v[38:39], v[0:1] op_sel_hi:[1,0]
	v_pk_mul_f32 v[30:31], v[34:35], v[0:1] op_sel_hi:[1,0]
	v_pk_mul_f32 v[2:3], v[2:3], v[42:43]
	v_pk_mul_f32 v[4:5], v[28:29], v[4:5]
	v_pk_mul_f32 v[28:29], v[32:33], v[0:1] op_sel_hi:[1,0]
	v_pk_mul_f32 v[20:21], v[30:31], v[20:21]
	v_pk_mul_f32 v[28:29], v[28:29], v[40:41]
	v_cvt_pk_bf16_f32 v2, v2, v3
	v_cvt_pk_bf16_f32 v3, v4, v5
	v_cvt_pk_bf16_f32 v5, v20, v21
	v_add_co_u32_e32 v20, vcc, s20, v10
	v_cvt_pk_bf16_f32 v4, v28, v29
	s_nop 0
	v_addc_co_u32_e32 v21, vcc, -1, v11, vcc
	global_store_dwordx4 v[20:21], v[2:5], off offset:-1024
	global_load_dwordx4 v[2:5], v[8:9], off offset:16
	s_nop 0
	global_load_dwordx4 v[28:31], v[8:9], off
	v_lshl_add_u64 v[10:11], v[10:11], 0, s[12:13]
	s_waitcnt vmcnt(1)
	v_pk_mul_f32 v[2:3], v[2:3], v[0:1] op_sel_hi:[1,0]
	s_waitcnt vmcnt(0)
	v_pk_mul_f32 v[28:29], v[28:29], v[0:1] op_sel_hi:[1,0]
	v_pk_mul_f32 v[14:15], v[2:3], v[14:15]
	v_pk_mul_f32 v[18:19], v[28:29], v[18:19]
	v_pk_mul_f32 v[28:29], v[30:31], v[0:1] op_sel_hi:[1,0]
	v_pk_mul_f32 v[2:3], v[4:5], v[0:1] op_sel_hi:[1,0]
	v_pk_mul_f32 v[16:17], v[28:29], v[16:17]
	v_pk_mul_f32 v[12:13], v[2:3], v[12:13]
	v_cvt_pk_bf16_f32 v2, v18, v19
	v_cvt_pk_bf16_f32 v3, v16, v17
	v_cvt_pk_bf16_f32 v4, v14, v15
	v_cvt_pk_bf16_f32 v5, v12, v13
	global_store_dwordx4 v[20:21], v[2:5], off
	s_cbranch_scc1 .LBB0_1149
